# stack: pipelined attention chunk body + combine row loop prefetch restored (invariant g loads hoisted, copies sunk behind one counted wait) + SGU weight loads hoisted ahead of the MFMA steps + norm lo
# speedup vs baseline: 1.0108x; 1.0108x over previous
; #define LAS __attribute__((address_space(3)))
; __device__ __forceinline__ void phase_norm(const Params& P, LAS unsigned char* lds, int l, int i, const void* xsrc, int src16, int out8) {
;     ...
;     f32x4 nx[8];
; #pragma unroll
;     for (int j = 0; j < 8; ++j) nx[j] = (f32x4){0.f, 0.f, 0.f, 0.f};
;     const int G8 = (gridDim.x % 8 == 0 && (MTOK / 8) % (int)gridDim.x == 0) ? 1 : 0;
;     const int r0x = G8 ? (MTOK / 8) * ((int)blockIdx.x & 7) + ((int)blockIdx.x >> 3) * 8 + (tid >> 6) : gw, rsx = G8 ? NGW / 8 : NGW, rex = G8 ? (MTOK / 8) * (((int)blockIdx.x & 7) + 1) : MTOK;
;     if (r0x < rex) NRM_LOAD(nx, r0x);
;     ...
;         for (int j = 0; j < 8; ++j) { const int c = src16 ? (8 * (lane + 64 * (j >> 1)) + 4 * (j & 1)) : 4 * (lane + 64 * j);
;             const f32x4 gg = *(const LAS f32x4*)(gs + b * DM + c), s0 = *(const LAS f32x4*)(shl + b * DM + c);
.LBB0_343:
	global_load_dwordx4 v[16:19], v[28:29], off
	global_load_dwordx4 v[20:23], v[28:29], off offset:1024
	global_load_dwordx4 v[24:27], v[28:29], off offset:2048
	s_nop 0
	global_load_dwordx4 v[28:31], v[28:29], off offset:3072
	v_cmp_eq_u32_e64 s[42:43], 0, v42
	v_or_b32_e32 v2, 4, v36
	v_or_b32_e32 v37, 0x100, v40
	v_or_b32_e32 v41, 0x204, v36
	v_or_b32_e32 v42, 0x300, v40
	v_or_b32_e32 v43, 0x404, v36
	v_or_b32_e32 v44, 0x500, v40
	v_or_b32_e32 v36, 0x604, v36
	v_or_b32_e32 v45, 0x700, v40
	s_and_b64 s[8:9], s[8:9], exec
	v_readlane_b32 s4, v252, 54
	v_cndmask_b32_e64 v2, v2, v37, s[38:39]
	v_cndmask_b32_e64 v40, v41, v42, s[38:39]
	v_cndmask_b32_e64 v42, v43, v44, s[38:39]
	v_cndmask_b32_e64 v44, v36, v45, s[38:39]
	v_mov_b64_e32 v[36:37], 0x3e1000
	s_cselect_b32 s8, s4, s97
	v_lshl_add_u64 v[46:47], v[62:63], 2, v[36:37]
	v_lshlrev_b64 v[36:37], 11, v[62:63]
	s_mov_b64 s[18:19], 0x13ff1000
	v_mov_b32_e32 v41, v3
	v_mov_b32_e32 v43, v3
	v_mov_b32_e32 v45, v3
	v_lshl_add_u64 v[48:49], v[48:49], 0, v[36:37]
	v_lshl_add_u64 v[36:37], v[36:37], 0, s[18:19]
	s_add_i32 s3, s8, s3
	v_lshl_add_u64 v[50:51], v[36:37], 0, v[2:3]
	v_lshl_add_u64 v[52:53], v[36:37], 0, v[40:41]
	v_lshl_add_u64 v[54:55], v[36:37], 0, v[42:43]
	v_lshl_add_u64 v[56:57], v[36:37], 0, v[44:45]
	v_add_u32_e32 v36, s3, v58
	v_ashrrev_i32_e32 v37, 31, v36
	v_lshlrev_b64 v[58:59], 13, v[36:37]
	v_readlane_b32 s4, v250, 55
	s_ashr_i32 s9, s8, 31
	v_lshl_add_u64 v[38:39], v[38:39], 2, v[58:59]
	v_readlane_b32 s5, v250, 56
	v_lshlrev_b64 v[36:37], 12, v[36:37]
	v_mov_b32_e32 v72, 0
	s_lshl_b64 s[12:13], s[8:9], 2
	s_lshl_b64 s[20:21], s[8:9], 11
	v_lshl_add_u64 v[58:59], s[4:5], 0, v[38:39]
	s_lshl_b64 s[26:27], s[8:9], 13
	v_lshl_add_u64 v[60:61], v[60:61], 1, v[36:37]
	s_lshl_b64 s[52:53], s[8:9], 12
	s_mov_b64 s[54:55], 0
	v_mov_b32_e32 v73, v72
	v_mov_b32_e32 v74, v72
	v_mov_b32_e32 v75, v72
	v_mov_b32_e32 v86, v72
	v_mov_b32_e32 v87, v72
	v_mov_b32_e32 v84, v72
	v_mov_b32_e32 v85, v72
	v_mov_b32_e32 v82, v72
	v_mov_b32_e32 v83, v72
	v_mov_b32_e32 v80, v72
	v_mov_b32_e32 v81, v72
	v_mov_b32_e32 v66, v72
	v_mov_b32_e32 v67, v72
	v_mov_b32_e32 v64, v72
	v_mov_b32_e32 v65, v72
	s_waitcnt vmcnt(0)
	s_branch .LBB0_345

; __device__ __forceinline__ f32x4 cvt4(const f16x8 v, int hi) { return (f32x4){(float)v[4 * hi], (float)v[4 * hi + 1], (float)v[4 * hi + 2], (float)v[4 * hi + 3]}; }
; __device__ __forceinline__ void phase_norm(const Params& P, LAS unsigned char* lds, int l, int i, const void* xsrc, int src16, int out8) {
;     ...
;     for (int row = r0x; row < rex; row += rsx) {
;         const int b = row >> 12;
;         f32x4 v[8]; float ss = 0.f;
; #pragma unroll
;         for (int j = 0; j < 8; ++j) { if (src16) { if ((j & 1) == 0) { const f16x8 t = __builtin_bit_cast(f16x8, nx[j >> 1]); v[j] = cvt4(t, 0); v[j + 1] = cvt4(t, 1); } } else v[j] = nx[j]; }
;         if (row + rsx < rex) NRM_LOAD(nx, row + rsx);
.LBB0_345:
	s_and_b64 vcc, exec, s[40:41]
	s_mov_b64 s[44:45], -1
	s_cbranch_vccnz .LBB0_347
	s_nop 0
	v_cvt_f32_f16_sdwa v71, v16 dst_sel:DWORD dst_unused:UNUSED_PAD src0_sel:WORD_1
	v_cvt_f32_f16_e32 v70, v16
	v_cvt_f32_f16_sdwa v69, v17 dst_sel:DWORD dst_unused:UNUSED_PAD src0_sel:WORD_1
	v_cvt_f32_f16_e32 v68, v17
	v_cvt_f32_f16_sdwa v37, v18 dst_sel:DWORD dst_unused:UNUSED_PAD src0_sel:WORD_1
	v_cvt_f32_f16_e32 v36, v18
	v_cvt_f32_f16_sdwa v39, v19 dst_sel:DWORD dst_unused:UNUSED_PAD src0_sel:WORD_1
	v_cvt_f32_f16_e32 v38, v19
	s_mov_b64 s[44:45], 0
.LBB0_347:
	s_andn2_b64 vcc, exec, s[44:45]
	s_cbranch_vccnz .LBB0_349
	s_nop 0
	v_mov_b32_e32 v70, v16
	v_mov_b32_e32 v71, v17
	v_mov_b32_e32 v68, v18
	v_mov_b32_e32 v69, v19
	v_mov_b32_e32 v36, v72
	v_mov_b32_e32 v37, v73
	v_mov_b32_e32 v38, v74
	v_mov_b32_e32 v39, v75
.LBB0_349:
	s_nop 0
	v_cndmask_b32_e64 v73, v39, v23, s[38:39]
	v_cndmask_b32_e64 v72, v38, v22, s[38:39]
	v_cndmask_b32_e64 v75, v37, v21, s[38:39]
	v_cndmask_b32_e64 v74, v36, v20, s[38:39]
	s_and_b64 vcc, exec, s[40:41]
	s_mov_b64 s[44:45], -1
	s_cbranch_vccnz .LBB0_351
	v_cvt_f32_f16_sdwa v77, v20 dst_sel:DWORD dst_unused:UNUSED_PAD src0_sel:WORD_1
	v_cvt_f32_f16_e32 v76, v20
	v_cvt_f32_f16_sdwa v79, v21 dst_sel:DWORD dst_unused:UNUSED_PAD src0_sel:WORD_1
	v_cvt_f32_f16_e32 v78, v21
	v_cvt_f32_f16_sdwa v37, v22 dst_sel:DWORD dst_unused:UNUSED_PAD src0_sel:WORD_1
	v_cvt_f32_f16_e32 v36, v22
	v_cvt_f32_f16_sdwa v39, v23 dst_sel:DWORD dst_unused:UNUSED_PAD src0_sel:WORD_1
	v_cvt_f32_f16_e32 v38, v23
	s_mov_b64 s[44:45], 0
.LBB0_351:
	s_andn2_b64 vcc, exec, s[44:45]
	s_cbranch_vccnz .LBB0_353
	s_nop 0
	v_mov_b32_e32 v76, v24
	v_mov_b32_e32 v77, v25
	v_mov_b32_e32 v78, v26
	v_mov_b32_e32 v79, v27
	v_mov_b32_e32 v36, v86
	v_mov_b32_e32 v37, v87
	v_mov_b32_e32 v38, v84
	v_mov_b32_e32 v39, v85
.LBB0_353:
	s_nop 0
	v_cndmask_b32_e64 v85, v39, v31, s[38:39]
	v_cndmask_b32_e64 v84, v38, v30, s[38:39]
	v_cndmask_b32_e64 v87, v37, v29, s[38:39]
	v_cndmask_b32_e64 v86, v36, v28, s[38:39]
	s_and_b64 vcc, exec, s[40:41]
	s_mov_b64 s[44:45], -1
	s_cbranch_vccnz .LBB0_355
	v_cvt_f32_f16_sdwa v89, v24 dst_sel:DWORD dst_unused:UNUSED_PAD src0_sel:WORD_1
	v_cvt_f32_f16_e32 v88, v24
	v_cvt_f32_f16_sdwa v91, v25 dst_sel:DWORD dst_unused:UNUSED_PAD src0_sel:WORD_1
	v_cvt_f32_f16_e32 v90, v25
	v_cvt_f32_f16_sdwa v37, v26 dst_sel:DWORD dst_unused:UNUSED_PAD src0_sel:WORD_1
	v_cvt_f32_f16_e32 v36, v26
	v_cvt_f32_f16_sdwa v39, v27 dst_sel:DWORD dst_unused:UNUSED_PAD src0_sel:WORD_1
	v_cvt_f32_f16_e32 v38, v27
	s_mov_b64 s[44:45], 0

; #define LAS __attribute__((address_space(3)))
; __device__ __forceinline__ void sgu_item(const Params& P, LAS unsigned char* lds, int l, int item) {
;     ...
;     for (int ti = 0; ti < 2; ++ti) {
;     ...
; #pragma unroll
;         for (int rq = 0; rq < 4; ++rq) *(LAS f32x4*)(mix + t * 132 + 32 * cb + 8 * rq + 4 * hf) = (f32x4){acc[4 * rq], acc[4 * rq + 1], acc[4 * rq + 2], acc[4 * rq + 3]};
;     }
.LBB0_953:
	s_waitcnt vmcnt(0)
	s_xor_b64 s[8:9], s[8:9], -1
	v_mad_i32_i24 v2, v105, s4, v42
	s_mov_b32 s19, 1
	s_andn2_b64 vcc, exec, s[8:9]
	s_mov_b64 s[8:9], 0
	s_nop 5
	ds_write_b128 v2, v[4:7] offset:34816
	ds_write_b128 v2, v[8:11] offset:34848
	ds_write_b128 v2, v[12:15] offset:34880
	ds_write_b128 v2, v[16:19] offset:34912
	s_cbranch_vccz .LBB0_883

; #define LAS __attribute__((address_space(3)))
; __device__ __forceinline__ void sgu_item(const Params& P, LAS unsigned char* lds, int l, int item) {
;     ...
;         const int tb = pr ? (1 + ti) : (3 * ti), t = 32 * tb + ln;
;         f32x16 acc;
; #pragma unroll
;         for (int r = 0; r < 16; ++r) acc[r] = 0.f;
;         const float* wrow = P.sgu_w + (((size_t)l * NH + h) * 128 + t) * 128 + 8 * hf;
;         const LAS f16* vrow = vhT + (32 * cb + ln) * 136 + 8 * hf;
; #pragma unroll
;         for (int st = 0; st < 8; ++st) if (st < 2 * (tb + 1)) {
;             const f32x4 w0 = *(const f32x4*)(wrow + 16 * st), w1 = *(const f32x4*)(wrow + 16 * st + 4);
;             f16x8 wf;
; #pragma unroll
;             for (int e = 0; e < 4; ++e) { const int s0 = 16 * st + 8 * hf + e; wf[e] = (s0 <= t) ? (f16)w0[e] : (f16)0.f; wf[4 + e] = (s0 + 4 <= t) ? (f16)w1[e] : (f16)0.f; }
;             const f16x8 vf = *(const LAS f16x8*)(vrow + 16 * st);
;             acc = __builtin_amdgcn_mfma_f32_32x32x16_f16(vf, wf, acc, 0, 0, 0);
;         }
.LBB0_958:
	v_lshl_or_b32 v105, s2, 5, v35
	v_add_u32_e32 v2, s3, v105
	v_lshlrev_b64 v[4:5], 9, v[2:3]
	v_lshl_add_u64 v[38:39], v[36:37], 0, v[4:5]
	global_load_dwordx4 v[4:7], v[38:39], off offset:16
	global_load_dwordx4 v[8:11], v[38:39], off
	global_load_dwordx4 v[110:113], v[38:39], off offset:80
	global_load_dwordx4 v[114:117], v[38:39], off offset:64
	global_load_dwordx4 v[118:121], v[38:39], off offset:144
	global_load_dwordx4 v[122:125], v[38:39], off offset:128
	global_load_dwordx4 v[126:129], v[38:39], off offset:208
	global_load_dwordx4 v[130:133], v[38:39], off offset:192
	global_load_dwordx4 v[134:137], v[38:39], off offset:272
	global_load_dwordx4 v[138:141], v[38:39], off offset:256
	global_load_dwordx4 v[142:145], v[38:39], off offset:336
	global_load_dwordx4 v[146:149], v[38:39], off offset:320
	global_load_dwordx4 v[150:153], v[38:39], off offset:400
	global_load_dwordx4 v[154:157], v[38:39], off offset:384
	global_load_dwordx4 v[158:161], v[38:39], off offset:464
	global_load_dwordx4 v[176:179], v[38:39], off offset:448
	v_cmp_le_u32_e32 vcc, v40, v105
	s_cmp_lg_u32 s2, 0
	s_cselect_b64 s[12:13], -1, 0
	s_cmp_eq_u32 s2, 0
	s_waitcnt vmcnt(15)
	v_cvt_f16_f32_e32 v4, v4
	s_waitcnt vmcnt(14)
	v_cvt_f16_f32_e32 v2, v8
	v_cvt_f16_f32_e32 v8, v9
	v_cvt_f16_f32_e32 v5, v5
	v_cvt_f16_f32_e32 v9, v10
	v_cndmask_b32_e32 v2, 0, v2, vcc
	v_cmp_le_u32_e32 vcc, v43, v105
	v_cvt_f16_f32_e32 v6, v6
	v_cvt_f16_f32_e32 v10, v11
	v_cndmask_b32_e32 v4, 0, v4, vcc
	v_cmp_lt_u32_e32 vcc, v40, v105
	v_cvt_f16_f32_e32 v7, v7
	s_nop 0
	v_cndmask_b32_e32 v8, 0, v8, vcc
	v_cmp_le_u32_e32 vcc, v44, v105
	s_nop 1
	v_cndmask_b32_e32 v5, 0, v5, vcc
	v_cmp_le_u32_e32 vcc, v45, v105
	s_nop 1
	v_cndmask_b32_e32 v9, 0, v9, vcc
	v_cmp_le_u32_e32 vcc, v46, v105
	s_nop 1
	v_cndmask_b32_e32 v6, 0, v6, vcc
	v_cmp_le_u32_e32 vcc, v47, v105
	s_nop 1
	v_cndmask_b32_e32 v10, 0, v10, vcc
	v_cmp_le_u32_e32 vcc, v48, v105
	s_nop 1
	v_cndmask_b32_e32 v7, 0, v7, vcc
	v_pack_b32_f16 v7, v6, v7
	v_pack_b32_f16 v6, v4, v5
	v_pack_b32_f16 v5, v9, v10
	v_pack_b32_f16 v4, v2, v8
	ds_read_b128 v[8:11], v41
	ds_read_b128 v[20:23], v41 offset:32
	s_nop 0
	s_nop 0
	v_cmp_le_u32_e32 vcc, v49, v105
	s_waitcnt lgkmcnt(1)
	v_mfma_f32_32x32x16_f16 v[4:19], v[8:11], v[4:7], 0
	s_waitcnt vmcnt(12)
	v_cvt_f16_f32_e32 v24, v110
	s_nop 0
	v_cvt_f16_f32_e32 v2, v114
	v_cvt_f16_f32_e32 v106, v115
	v_cvt_f16_f32_e32 v25, v111
	v_cvt_f16_f32_e32 v107, v116
	v_cndmask_b32_e32 v2, 0, v2, vcc
	v_cmp_le_u32_e32 vcc, v50, v105
	v_cvt_f16_f32_e32 v26, v112
	v_cvt_f16_f32_e32 v108, v117
	v_cndmask_b32_e32 v24, 0, v24, vcc
	v_cmp_le_u32_e32 vcc, v51, v105
	v_cvt_f16_f32_e32 v27, v113
	s_nop 0
	v_cndmask_b32_e32 v106, 0, v106, vcc
	v_cmp_le_u32_e32 vcc, v52, v105
	s_nop 1
	v_cndmask_b32_e32 v25, 0, v25, vcc
	v_cmp_le_u32_e32 vcc, v53, v105
	s_nop 1
	v_cndmask_b32_e32 v107, 0, v107, vcc
	v_cmp_le_u32_e32 vcc, v54, v105
	s_nop 1
	v_cndmask_b32_e32 v26, 0, v26, vcc
	v_cmp_le_u32_e32 vcc, v55, v105
	s_nop 1
	v_cndmask_b32_e32 v108, 0, v108, vcc
	v_cmp_le_u32_e32 vcc, v56, v105
	s_nop 1
	v_cndmask_b32_e32 v27, 0, v27, vcc
	v_pack_b32_f16 v27, v26, v27
	v_pack_b32_f16 v26, v24, v25
	v_pack_b32_f16 v25, v107, v108
	v_pack_b32_f16 v24, v2, v106
	s_waitcnt lgkmcnt(0)
	s_nop 0
	v_mfma_f32_32x32x16_f16 v[4:19], v[20:23], v[24:27], v[4:19]
	s_cbranch_scc1 .LBB0_960
	s_nop 0
	s_nop 0
	v_cmp_le_u32_e32 vcc, v57, v105
	s_waitcnt vmcnt(10)
	v_cvt_f16_f32_e32 v20, v118
	s_nop 0
	v_cvt_f16_f32_e32 v2, v122
	v_cvt_f16_f32_e32 v24, v123
	v_cvt_f16_f32_e32 v21, v119
	v_cvt_f16_f32_e32 v25, v124
	v_cndmask_b32_e32 v2, 0, v2, vcc
	v_cmp_le_u32_e32 vcc, v58, v105
	v_cvt_f16_f32_e32 v22, v120
	v_cvt_f16_f32_e32 v26, v125
	v_cndmask_b32_e32 v20, 0, v20, vcc
	v_cmp_le_u32_e32 vcc, v59, v105
	v_cvt_f16_f32_e32 v23, v121
	s_nop 0
	v_cndmask_b32_e32 v24, 0, v24, vcc
	v_cmp_le_u32_e32 vcc, v60, v105
	s_nop 1
	v_cndmask_b32_e32 v21, 0, v21, vcc
	v_cmp_le_u32_e32 vcc, v61, v105
	s_nop 1
	v_cndmask_b32_e32 v25, 0, v25, vcc
	v_cmp_le_u32_e32 vcc, v62, v105
	s_nop 1
	v_cndmask_b32_e32 v22, 0, v22, vcc
	v_cmp_le_u32_e32 vcc, v63, v105
	s_nop 1
	v_cndmask_b32_e32 v26, 0, v26, vcc
	v_cmp_le_u32_e32 vcc, v64, v105
	s_nop 1
	v_cndmask_b32_e32 v23, 0, v23, vcc
	v_pack_b32_f16 v23, v22, v23
	v_pack_b32_f16 v22, v20, v21
	v_pack_b32_f16 v21, v25, v26
	v_pack_b32_f16 v20, v2, v24
	ds_read_b128 v[24:27], v41 offset:64
	s_waitcnt lgkmcnt(0)
	v_mfma_f32_32x32x16_f16 v[4:19], v[24:27], v[20:23], v[4:19]
.LBB0_960:
	s_andn2_b64 vcc, exec, s[12:13]
	s_cbranch_vccnz .LBB0_962
	s_nop 0
	s_nop 0
	v_cmp_le_u32_e32 vcc, v65, v105
	s_waitcnt vmcnt(8)
	v_cvt_f16_f32_e32 v20, v126
	s_nop 0
	v_cvt_f16_f32_e32 v2, v130
	v_cvt_f16_f32_e32 v24, v131
	v_cvt_f16_f32_e32 v21, v127
	v_cvt_f16_f32_e32 v25, v132
	v_cndmask_b32_e32 v2, 0, v2, vcc
	v_cmp_le_u32_e32 vcc, v66, v105
	v_cvt_f16_f32_e32 v22, v128
	v_cvt_f16_f32_e32 v26, v133
	v_cndmask_b32_e32 v20, 0, v20, vcc
	v_cmp_le_u32_e32 vcc, v67, v105
	v_cvt_f16_f32_e32 v23, v129
	s_nop 0
	v_cndmask_b32_e32 v24, 0, v24, vcc
	v_cmp_le_u32_e32 vcc, v68, v105
	s_nop 1
	v_cndmask_b32_e32 v21, 0, v21, vcc
	v_cmp_le_u32_e32 vcc, v69, v105
	s_nop 1
	v_cndmask_b32_e32 v25, 0, v25, vcc
	v_cmp_le_u32_e32 vcc, v70, v105
	s_nop 1
	v_cndmask_b32_e32 v22, 0, v22, vcc
	v_cmp_le_u32_e32 vcc, v71, v105
	s_nop 1
	v_cndmask_b32_e32 v26, 0, v26, vcc
	v_cmp_le_u32_e32 vcc, v72, v105
	s_nop 1
	v_cndmask_b32_e32 v23, 0, v23, vcc
	v_pack_b32_f16 v23, v22, v23
	v_pack_b32_f16 v22, v20, v21
	v_pack_b32_f16 v21, v25, v26
	v_pack_b32_f16 v20, v2, v24
	ds_read_b128 v[24:27], v41 offset:96
	s_waitcnt lgkmcnt(0)
	v_mfma_f32_32x32x16_f16 v[4:19], v[24:27], v[20:23], v[4:19]

; #define LAS __attribute__((address_space(3)))
; __device__ __forceinline__ void sgu_item(const Params& P, LAS unsigned char* lds, int l, int item) {
;     ...
;         for (int st = 0; st < 8; ++st) if (st < 2 * (tb + 1)) {
;             const f32x4 w0 = *(const f32x4*)(wrow + 16 * st), w1 = *(const f32x4*)(wrow + 16 * st + 4);
;             f16x8 wf;
; #pragma unroll
;             for (int e = 0; e < 4; ++e) { const int s0 = 16 * st + 8 * hf + e; wf[e] = (s0 <= t) ? (f16)w0[e] : (f16)0.f; wf[4 + e] = (s0 + 4 <= t) ? (f16)w1[e] : (f16)0.f; }
;             const f16x8 vf = *(const LAS f16x8*)(vrow + 16 * st);
;             acc = __builtin_amdgcn_mfma_f32_32x32x16_f16(vf, wf, acc, 0, 0, 0);
;         }
.LBB0_966:
	s_nop 0
	s_nop 0
	v_cmp_le_u32_e32 vcc, v73, v105
	s_waitcnt vmcnt(6)
	v_cvt_f16_f32_e32 v20, v134
	s_nop 0
	v_cvt_f16_f32_e32 v2, v138
	v_cvt_f16_f32_e32 v24, v139
	v_cvt_f16_f32_e32 v21, v135
	v_cvt_f16_f32_e32 v25, v140
	v_cndmask_b32_e32 v2, 0, v2, vcc
	v_cmp_le_u32_e32 vcc, v74, v105
	v_cvt_f16_f32_e32 v22, v136
	v_cvt_f16_f32_e32 v26, v141
	v_cndmask_b32_e32 v20, 0, v20, vcc
	v_cmp_le_u32_e32 vcc, v75, v105
	v_cvt_f16_f32_e32 v23, v137
	s_nop 0
	v_cndmask_b32_e32 v24, 0, v24, vcc
	v_cmp_le_u32_e32 vcc, v76, v105
	s_nop 1
	v_cndmask_b32_e32 v21, 0, v21, vcc
	v_cmp_le_u32_e32 vcc, v77, v105
	s_nop 1
	v_cndmask_b32_e32 v25, 0, v25, vcc
	v_cmp_le_u32_e32 vcc, v78, v105
	s_nop 1
	v_cndmask_b32_e32 v22, 0, v22, vcc
	v_cmp_le_u32_e32 vcc, v79, v105
	s_nop 1
	v_cndmask_b32_e32 v26, 0, v26, vcc
	v_cmp_le_u32_e32 vcc, v80, v105
	s_nop 1
	v_cndmask_b32_e32 v23, 0, v23, vcc
	v_pack_b32_f16 v23, v22, v23
	v_pack_b32_f16 v22, v20, v21
	v_pack_b32_f16 v21, v25, v26
	v_pack_b32_f16 v20, v2, v24
	ds_read_b128 v[24:27], v41 offset:128
	s_waitcnt lgkmcnt(0)
	v_mfma_f32_32x32x16_f16 v[4:19], v[24:27], v[20:23], v[4:19]
	s_andn2_b64 vcc, exec, s[12:13]
	s_cbranch_vccnz .LBB0_964
.LBB0_967:
	s_nop 0
	s_nop 0
	v_cmp_le_u32_e32 vcc, v81, v105
	s_waitcnt vmcnt(4)
	v_cvt_f16_f32_e32 v20, v142
	s_nop 0
	v_cvt_f16_f32_e32 v2, v146
	v_cvt_f16_f32_e32 v24, v147
	v_cvt_f16_f32_e32 v21, v143
	v_cvt_f16_f32_e32 v25, v148
	v_cndmask_b32_e32 v2, 0, v2, vcc
	v_cmp_le_u32_e32 vcc, v82, v105
	v_cvt_f16_f32_e32 v22, v144
	v_cvt_f16_f32_e32 v26, v149
	v_cndmask_b32_e32 v20, 0, v20, vcc
	v_cmp_le_u32_e32 vcc, v83, v105
	v_cvt_f16_f32_e32 v23, v145
	s_nop 0
	v_cndmask_b32_e32 v24, 0, v24, vcc
	v_cmp_le_u32_e32 vcc, v84, v105
	s_nop 1
	v_cndmask_b32_e32 v21, 0, v21, vcc
	v_cmp_le_u32_e32 vcc, v85, v105
	s_nop 1
	v_cndmask_b32_e32 v25, 0, v25, vcc
	v_cmp_le_u32_e32 vcc, v86, v105
	s_nop 1
	v_cndmask_b32_e32 v22, 0, v22, vcc
	v_cmp_le_u32_e32 vcc, v87, v105
	s_nop 1
	v_cndmask_b32_e32 v26, 0, v26, vcc
	v_cmp_le_u32_e32 vcc, v88, v105
	s_nop 1
	v_cndmask_b32_e32 v23, 0, v23, vcc
	v_pack_b32_f16 v23, v22, v23
	v_pack_b32_f16 v22, v20, v21
	v_pack_b32_f16 v21, v25, v26
	v_pack_b32_f16 v20, v2, v24
	ds_read_b128 v[24:27], v41 offset:160
	s_waitcnt lgkmcnt(0)
	v_mfma_f32_32x32x16_f16 v[4:19], v[24:27], v[20:23], v[4:19]
	s_cmp_gt_u32 s2, 2
	s_cselect_b64 s[12:13], -1, 0
	s_cmp_lt_u32 s2, 3
	s_cbranch_scc1 .LBB0_965
.LBB0_968:
	s_nop 0
	s_nop 0
	v_cmp_le_u32_e32 vcc, v89, v105
	s_waitcnt vmcnt(2)
	v_cvt_f16_f32_e32 v20, v150
	s_nop 0
	v_cvt_f16_f32_e32 v2, v154
	v_cvt_f16_f32_e32 v24, v155
	v_cvt_f16_f32_e32 v21, v151
	v_cvt_f16_f32_e32 v25, v156
	v_cndmask_b32_e32 v2, 0, v2, vcc
	v_cmp_le_u32_e32 vcc, v90, v105
	v_cvt_f16_f32_e32 v22, v152
	v_cvt_f16_f32_e32 v26, v157
	v_cndmask_b32_e32 v20, 0, v20, vcc
	v_cmp_le_u32_e32 vcc, v91, v105
	v_cvt_f16_f32_e32 v23, v153
	s_nop 0
	v_cndmask_b32_e32 v24, 0, v24, vcc
	v_cmp_le_u32_e32 vcc, v92, v105
	s_nop 1
	v_cndmask_b32_e32 v21, 0, v21, vcc
	v_cmp_le_u32_e32 vcc, v93, v105
	s_nop 1
	v_cndmask_b32_e32 v25, 0, v25, vcc
	v_cmp_le_u32_e32 vcc, v94, v105
	s_nop 1
	v_cndmask_b32_e32 v22, 0, v22, vcc
	v_cmp_le_u32_e32 vcc, v95, v105
	s_nop 1
	v_cndmask_b32_e32 v26, 0, v26, vcc
	v_cmp_le_u32_e32 vcc, v96, v105
	s_nop 1
	v_cndmask_b32_e32 v23, 0, v23, vcc
	v_pack_b32_f16 v23, v22, v23
	v_pack_b32_f16 v22, v20, v21
	v_pack_b32_f16 v21, v25, v26
	v_pack_b32_f16 v20, v2, v24
	ds_read_b128 v[24:27], v41 offset:192
	s_waitcnt lgkmcnt(0)
	v_mfma_f32_32x32x16_f16 v[4:19], v[24:27], v[20:23], v[4:19]
	s_andn2_b64 vcc, exec, s[12:13]
	s_cbranch_vccnz .LBB0_953
.LBB0_969:
	s_nop 0
	s_nop 0
	v_cmp_le_u32_e32 vcc, v97, v105
	s_waitcnt vmcnt(0)
	v_cvt_f16_f32_e32 v20, v158
	s_nop 0
	v_cvt_f16_f32_e32 v2, v176
	v_cvt_f16_f32_e32 v24, v177
	v_cvt_f16_f32_e32 v21, v159
	v_cvt_f16_f32_e32 v25, v178
	v_cndmask_b32_e32 v2, 0, v2, vcc
	v_cmp_le_u32_e32 vcc, v98, v105
	v_cvt_f16_f32_e32 v22, v160
	v_cvt_f16_f32_e32 v26, v179
	v_cndmask_b32_e32 v20, 0, v20, vcc
	v_cmp_le_u32_e32 vcc, v99, v105
	v_cvt_f16_f32_e32 v23, v161
	s_nop 0
	v_cndmask_b32_e32 v24, 0, v24, vcc
	v_cmp_le_u32_e32 vcc, v100, v105
	s_nop 1
	v_cndmask_b32_e32 v21, 0, v21, vcc
	v_cmp_le_u32_e32 vcc, v101, v105
	s_nop 1
	v_cndmask_b32_e32 v25, 0, v25, vcc
	v_cmp_le_u32_e32 vcc, v102, v105
	s_nop 1
	v_cndmask_b32_e32 v22, 0, v22, vcc
	v_cmp_le_u32_e32 vcc, v103, v105
	s_nop 1
	v_cndmask_b32_e32 v26, 0, v26, vcc
	v_cmp_le_u32_e32 vcc, v104, v105
	s_nop 1
	v_cndmask_b32_e32 v23, 0, v23, vcc
	v_pack_b32_f16 v23, v22, v23
	v_pack_b32_f16 v22, v20, v21
	v_pack_b32_f16 v21, v25, v26
	v_pack_b32_f16 v20, v2, v24
	ds_read_b128 v[24:27], v41 offset:224
	s_waitcnt lgkmcnt(0)
	v_mfma_f32_32x32x16_f16 v[4:19], v[24:27], v[20:23], v[4:19]
	s_branch .LBB0_953

; __device__ __forceinline__ void phase_combine(const Params& P, int l, bool write_lo) {
;     int tid_ = threadIdx.x; asm volatile("" : "+v"(tid_)); const int tid = tid_, lane = tid & 63, gw = blockIdx.x * 8 + (tid >> 6), NGW = gridDim.x * 8;
;     const f16* yraw = (const f16*)(P.ws + WS_BIG + BIG_YRAW);
;     const float* part = (const float*)(P.ws + WS_BIG + BIG_PART);
;     const float* lpart = (const float*)(P.ws + WS_LPART);
;     const float* og = P.out_norm_g + (size_t)l * DM;
;     f16* yh = (f16*)(P.ws + WS_XN); f16* yl = (f16*)(P.ws + WS_XN + XN_HALF);
;     f16x8 nraw; f32x2 no0[4], no1[4]; float nL0[4], nL1[4];
;     ...
;     const int G8 = (gridDim.x % 8 == 0 && (MTOK / 8) % (int)gridDim.x == 0) ? 1 : 0;
;     const int r0x = G8 ? (MTOK / 8) * ((int)blockIdx.x & 7) + ((int)blockIdx.x >> 3) * 8 + (tid >> 6) : gw, rsx = G8 ? NGW / 8 : NGW, rex = G8 ? (MTOK / 8) * (((int)blockIdx.x & 7) + 1) : MTOK;
;     if (r0x < rex) CMB_LOAD(r0x);
;     ...
;             const f32x4 g0 = *(const f32x4*)(og + GW * g + 8 * lane), g1 = *(const f32x4*)(og + GW * g + 8 * lane + 4);
;     ...
;         for (int h = 0; h < 4; ++h) { const int c = 2 * GW + 128 * h + 2 * lane; const f32x2 gg = *(const f32x2*)(og + c);
.LBB0_1040:
	s_or_b64 exec, exec, s[12:13]
	s_and_b64 s[8:9], s[8:9], exec
	v_readlane_b32 s3, v252, 54
	v_readlane_b32 s4, v247, 31
	s_cselect_b32 s8, s3, s97
	s_lshl_b32 s56, s4, 11
	s_lshl_b64 s[12:13], s[56:57], 2
	v_readlane_b32 s60, v251, 0
	v_lshlrev_b32_e32 v5, 1, v21
	v_readlane_b32 s61, v251, 1
	s_add_u32 s12, s60, s12
	s_addc_u32 s13, s61, s13
	v_lshlrev_b32_e32 v2, 2, v2
	v_lshlrev_b32_e32 v5, 2, v5
	v_lshl_add_u64 v[40:41], s[12:13], 0, v[2:3]
	v_or_b32_e32 v2, 0x1000, v5
	v_lshl_add_u64 v[42:43], s[12:13], 0, v[2:3]
	v_or_b32_e32 v2, 0x1200, v5
	v_lshl_add_u64 v[44:45], s[12:13], 0, v[2:3]
	v_or_b32_e32 v2, 0x1400, v5
	v_lshl_add_u64 v[46:47], s[12:13], 0, v[2:3]
	v_or_b32_e32 v2, 0x1600, v5
	v_lshl_add_u64 v[48:49], s[12:13], 0, v[2:3]
	v_lshlrev_b32_e32 v2, 2, v21
	v_mov_b32_e32 v5, v3
	v_lshl_add_u64 v[50:51], v[6:7], 0, v[2:3]
	v_lshl_add_u64 v[6:7], v[6:7], 0, v[4:5]
	s_mov_b64 s[20:21], 0x13ff1400
	s_add_i32 s2, s8, s2
	v_lshl_add_u64 v[52:53], v[6:7], 0, s[20:21]
	v_add_u32_e32 v6, s2, v20
	v_ashrrev_i32_e32 v7, 31, v6
	v_readlane_b32 s5, v247, 32
	v_lshlrev_b32_e32 v37, 2, v6
	v_lshlrev_b64 v[6:7], 12, v[6:7]
	v_or_b32_e32 v6, v6, v4
	s_mov_b64 s[4:5], 0x2dff1400
	s_ashr_i32 s9, s8, 31
	v_lshl_add_u64 v[54:55], v[6:7], 0, s[4:5]
	s_waitcnt vmcnt(8)
	v_mov_b64_e32 v[20:21], v[32:33]
	s_waitcnt vmcnt(1)
	v_mov_b64_e32 v[4:5], v[12:13]
	s_waitcnt vmcnt(0)
	v_mov_b64_e32 v[24:25], v[28:29]
	global_load_dwordx4 v[100:103], v[40:41], off offset:2064
	global_load_dwordx4 v[104:107], v[40:41], off offset:2048
	global_load_dwordx2 v[108:109], v[42:43], off
	global_load_dwordx2 v[110:111], v[44:45], off
	global_load_dwordx2 v[112:113], v[46:47], off
	global_load_dwordx2 v[114:115], v[48:49], off
	s_waitcnt vmcnt(0)
	s_lshl_b64 s[12:13], s[8:9], 12
	s_lshl_b32 s3, s8, 2
	s_mov_b64 s[20:21], 0
	s_mov_b64 s[26:27], s[90:91]
	v_mov_b64_e32 v[22:23], v[34:35]
	v_mov_b64_e32 v[6:7], v[14:15]
	v_mov_b64_e32 v[8:9], v[16:17]
	v_mov_b64_e32 v[10:11], v[18:19]
	v_mov_b64_e32 v[26:27], v[30:31]
	v_mov_b64_e32 v[62:63], v[64:65]
	v_mov_b64_e32 v[60:61], v[66:67]
	v_mov_b64_e32 v[58:59], v[68:69]
	v_mov_b64_e32 v[56:57], v[70:71]
	v_mov_b32_e32 v83, v84
	v_mov_b32_e32 v82, v85
	v_mov_b32_e32 v81, v86
	v_mov_b32_e32 v80, v87
	v_readlane_b32 s62, v251, 2
	v_readlane_b32 s63, v251, 3
	v_readlane_b32 s64, v251, 4
	v_readlane_b32 s65, v251, 5
	v_readlane_b32 s66, v251, 6
	v_readlane_b32 s67, v251, 7
	s_branch .LBB0_1043

; __device__ __forceinline__ f32x4 cvt4(const f16x8 v, int hi) { return (f32x4){(float)v[4 * hi], (float)v[4 * hi + 1], (float)v[4 * hi + 2], (float)v[4 * hi + 3]}; }
; __device__ __forceinline__ float wave_sum(float v) { v = row_sum16(v); return (rlanef(v, 0) + rlanef(v, 16)) + (rlanef(v, 32) + rlanef(v, 48)); }
; __device__ __forceinline__ void phase_combine(const Params& P, int l, bool write_lo) {
;     ...
;         const f16x8 raw = nraw; f32x2 o0[4], o1[4]; float L0[4], L1[4];
; #pragma unroll
;         for (int h = 0; h < 4; ++h) { o0[h] = no0[h]; o1[h] = no1[h]; L0[h] = nL0[h]; L1[h] = nL1[h]; }
;         if (row + rsx < rex) CMB_LOAD(row + rsx);
;         { const int g = 1;
;             const f32x4 v0 = cvt4(raw, 0), v1 = cvt4(raw, 1);
;             float ss = v0[0] * v0[0] + v0[1] * v0[1] + v0[2] * v0[2] + v0[3] * v0[3] + v1[0] * v1[0] + v1[1] * v1[1] + v1[2] * v1[2] + v1[3] * v1[3];
;             ss = wave_sum(ss);
;             const float rstd = 1.0f / sqrtf(ss * (1.0f / GW) + EPS);
;             const f32x4 g0 = *(const f32x4*)(og + GW * g + 8 * lane), g1 = *(const f32x4*)(og + GW * g + 8 * lane + 4);
;             *(f16x8*)(yh + (size_t)row * DM + GW * g + 8 * lane) = pack8(((v0 * rstd) * g0) * SA, ((v1 * rstd) * g1) * SA); }
;         f32x2 yc[4]; float ss = 0.f;
; #pragma unroll
;         for (int h = 0; h < 4; ++h) { yc[h] = (o0[h] + o1[h]) / (L0[h] + L1[h]); ss += yc[h][0] * yc[h][0] + yc[h][1] * yc[h][1]; }
.LBB0_1042:
	s_or_b64 exec, exec, s[38:39]
	v_cvt_f32_f16_sdwa v75, v32 dst_sel:DWORD dst_unused:UNUSED_PAD src0_sel:WORD_1
	v_cvt_f32_f16_e32 v74, v32
	v_cvt_f32_f16_sdwa v79, v33 dst_sel:DWORD dst_unused:UNUSED_PAD src0_sel:WORD_1
	v_cvt_f32_f16_e32 v78, v33
	v_cvt_f32_f16_sdwa v73, v34 dst_sel:DWORD dst_unused:UNUSED_PAD src0_sel:WORD_1
	v_cvt_f32_f16_e32 v72, v34
	v_pk_mul_f32 v[32:33], v[74:75], v[74:75]
	v_cvt_f32_f16_sdwa v77, v35 dst_sel:DWORD dst_unused:UNUSED_PAD src0_sel:WORD_1
	v_cvt_f32_f16_e32 v76, v35
	v_pk_mul_f32 v[34:35], v[78:79], v[78:79]
	v_add_f32_e32 v2, v32, v33
	v_add_f32_e32 v2, v34, v2
	v_pk_mul_f32 v[88:89], v[72:73], v[72:73]
	v_add_f32_e32 v2, v35, v2
	v_add_f32_e32 v2, v88, v2
	v_pk_mul_f32 v[90:91], v[76:77], v[76:77]
	v_add_f32_e32 v2, v89, v2
	v_add_f32_e32 v2, v90, v2
	v_add_f32_e32 v2, v91, v2
	s_and_b64 s[24:25], exec, vcc
	s_or_b64 s[20:21], s[24:25], s[20:21]
	v_add_f32_dpp v2, v2, v2 quad_perm:[1,0,3,2] row_mask:0xf bank_mask:0xf bound_ctrl:1
	v_pk_add_f32 v[12:13], v[70:71], v[12:13]
	v_pk_add_f32 v[14:15], v[68:69], v[14:15]
	v_add_f32_dpp v2, v2, v2 quad_perm:[2,3,0,1] row_mask:0xf bank_mask:0xf bound_ctrl:1
	v_pk_add_f32 v[16:17], v[66:67], v[16:17]
	v_pk_add_f32 v[18:19], v[64:65], v[18:19]
	v_add_f32_dpp v2, v2, v2 row_half_mirror row_mask:0xf bank_mask:0xf bound_ctrl:1
	v_add_u32_e32 v37, s3, v37
	s_nop 0
	s_nop 0
	v_add_f32_dpp v2, v2, v2 row_mirror row_mask:0xf bank_mask:0xf bound_ctrl:1
	s_nop 0
	s_nop 0
	v_readlane_b32 s2, v2, 16
	v_readlane_b32 s9, v2, 48
	v_readlane_b32 s24, v2, 0
	v_readlane_b32 s25, v2, 32
	v_mov_b32_e32 v32, s2
	v_mov_b32_e32 v33, s9
	v_pk_add_f32 v[32:33], s[24:25], v[32:33]
	s_nop 0
	s_nop 0
	v_add_f32_e32 v2, v32, v33
	v_fmamk_f32 v2, v2, 0x3b000000, v234
	v_cmp_gt_f32_e32 vcc, s83, v2
	v_mul_f32_e32 v32, 0x4f800000, v2
	s_nop 0
	s_nop 0
	v_cndmask_b32_e32 v2, v2, v32, vcc
	v_sqrt_f32_e32 v32, v2
	s_nop 0
	v_add_u32_e32 v33, -1, v32
	v_fma_f32 v34, -v33, v32, v2
	v_cmp_ge_f32_e64 s[42:43], 0, v34
	v_add_u32_e32 v34, 1, v32
	s_nop 0
	v_cndmask_b32_e64 v33, v32, v33, s[42:43]
	v_fma_f32 v32, -v34, v32, v2
	v_cmp_lt_f32_e64 s[42:43], 0, v32
	s_nop 1
	v_cndmask_b32_e64 v32, v33, v34, s[42:43]
	v_mul_f32_e32 v33, 0x37800000, v32
	v_cndmask_b32_e32 v32, v32, v33, vcc
	v_cmp_class_f32_e32 vcc, v2, v235
	s_nop 1
	v_cndmask_b32_e32 v2, v32, v2, vcc
	v_div_scale_f32 v32, s[24:25], v2, v2, 1.0
	v_rcp_f32_e32 v33, v32
	s_nop 0
	v_fma_f32 v34, -v32, v33, 1.0
	v_fmac_f32_e32 v33, v34, v33
	v_div_scale_f32 v34, vcc, 1.0, v2, 1.0
	v_mul_f32_e32 v35, v34, v33
	v_fma_f32 v88, -v32, v35, v34
	v_fmac_f32_e32 v35, v88, v33
	v_fma_f32 v32, -v32, v35, v34
	v_div_fmas_f32 v32, v32, v33, v35
	v_div_fixup_f32 v2, v32, v2, 1.0
	s_nop 0
	s_nop 0
	v_pk_mul_f32 v[78:79], v[78:79], v[2:3] op_sel_hi:[1,0]
	v_pk_mul_f32 v[74:75], v[74:75], v[2:3] op_sel_hi:[1,0]
	v_pk_mul_f32 v[76:77], v[76:77], v[2:3] op_sel_hi:[1,0]
	v_pk_mul_f32 v[72:73], v[72:73], v[2:3] op_sel_hi:[1,0]
	v_add_f32_e32 v2, v87, v28
	v_div_scale_f32 v28, s[24:25], v2, v2, v13
	s_nop 0
	s_nop 0
	v_pk_mul_f32 v[32:33], v[100:101], v[72:73]
	s_nop 0
	v_pk_mul_f32 v[74:75], v[104:105], v[74:75]
	v_pk_mul_f32 v[78:79], v[106:107], v[78:79]
	v_pk_mul_f32 v[34:35], v[102:103], v[76:77]
	v_pk_mul_f32 v[78:79], v[78:79], s[96:97] op_sel_hi:[1,0]
	v_pk_mul_f32 v[74:75], v[74:75], s[96:97] op_sel_hi:[1,0]
	v_pk_mul_f32 v[34:35], v[34:35], s[96:97] op_sel_hi:[1,0]
	v_pk_mul_f32 v[32:33], v[32:33], s[96:97] op_sel_hi:[1,0]
	v_cvt_pk_f16_f32 v35, v34, v35
	v_cvt_pk_f16_f32 v34, v32, v33
	v_cvt_pk_f16_f32 v33, v78, v79
	v_cvt_pk_f16_f32 v32, v74, v75
	v_lshl_add_u64 v[72:73], s[26:27], 0, v[52:53]
	global_store_dwordx4 v[72:73], v[32:35], off
	s_nop 1
	v_rcp_f32_e32 v32, v28
	s_nop 0
	v_fma_f32 v33, -v28, v32, 1.0
	v_fmac_f32_e32 v32, v33, v32
	v_div_scale_f32 v33, vcc, v13, v2, v13
	v_mul_f32_e32 v34, v33, v32
	v_fma_f32 v35, -v28, v34, v33
	v_fmac_f32_e32 v34, v35, v32
	v_fma_f32 v28, -v28, v34, v33
	v_div_fmas_f32 v28, v28, v32, v34
	v_div_fixup_f32 v13, v28, v2, v13
	v_div_scale_f32 v28, s[24:25], v2, v2, v12
	v_rcp_f32_e32 v32, v28
	s_nop 0
	v_fma_f32 v33, -v28, v32, 1.0
	v_fmac_f32_e32 v32, v33, v32
	v_div_scale_f32 v33, vcc, v12, v2, v12
	v_mul_f32_e32 v34, v33, v32
	v_fma_f32 v35, -v28, v34, v33
	v_fmac_f32_e32 v34, v35, v32
	v_fma_f32 v28, -v28, v34, v33
	v_div_fmas_f32 v28, v28, v32, v34
	v_div_fixup_f32 v12, v28, v2, v12
	v_add_f32_e32 v2, v86, v29
	v_div_scale_f32 v28, s[24:25], v2, v2, v15
	v_rcp_f32_e32 v29, v28
	s_nop 0
	v_fma_f32 v32, -v28, v29, 1.0
	v_fmac_f32_e32 v29, v32, v29
	v_div_scale_f32 v32, vcc, v15, v2, v15
	v_mul_f32_e32 v33, v32, v29
	v_fma_f32 v34, -v28, v33, v32
	v_fmac_f32_e32 v33, v34, v29
	v_fma_f32 v28, -v28, v33, v32
	v_div_fmas_f32 v28, v28, v29, v33
	v_div_fixup_f32 v15, v28, v2, v15
	v_div_scale_f32 v28, s[24:25], v2, v2, v14
	v_rcp_f32_e32 v29, v28
	s_nop 0
	v_fma_f32 v32, -v28, v29, 1.0
	v_fmac_f32_e32 v29, v32, v29
	v_div_scale_f32 v32, vcc, v14, v2, v14
	v_mul_f32_e32 v33, v32, v29
	v_fma_f32 v34, -v28, v33, v32
	v_fmac_f32_e32 v33, v34, v29
	v_fma_f32 v28, -v28, v33, v32
	v_div_fmas_f32 v28, v28, v29, v33
	v_div_fixup_f32 v14, v28, v2, v14
	v_mov_b32_e32 v32, v13
	v_mov_b32_e32 v33, v15
	v_add_f32_e32 v2, v85, v30
	v_mov_b32_e32 v28, v12
	v_mov_b32_e32 v29, v14
	v_pk_mul_f32 v[32:33], v[32:33], v[32:33]
; __device__ __forceinline__ float wave_sum(float v) { v = row_sum16(v); return (rlanef(v, 0) + rlanef(v, 16)) + (rlanef(v, 32) + rlanef(v, 48)); }
; __device__ __forceinline__ void phase_combine(const Params& P, int l, bool write_lo) {
;     ...
;         const f16x8 raw = nraw; f32x2 o0[4], o1[4]; float L0[4], L1[4];
; #pragma unroll
;         for (int h = 0; h < 4; ++h) { o0[h] = no0[h]; o1[h] = no1[h]; L0[h] = nL0[h]; L1[h] = nL1[h]; }
;     ...
;         for (int h = 0; h < 4; ++h) { yc[h] = (o0[h] + o1[h]) / (L0[h] + L1[h]); ss += yc[h][0] * yc[h][0] + yc[h][1] * yc[h][1]; }
;         ss = wave_sum(ss);
;         const float rstd = 1.0f / sqrtf(ss * (1.0f / GW) + EPS);
; #pragma unroll
;         for (int h = 0; h < 4; ++h) { const int c = 2 * GW + 128 * h + 2 * lane; const f32x2 gg = *(const f32x2*)(og + c);
;             const f32x2 y = ((yc[h] * rstd) * gg) * SA;
;             f16x2 hi, lo;
; #pragma unroll
;             for (int e = 0; e < 2; ++e) { const f16 hh = (f16)prb(y[e]); hi[e] = hh; lo[e] = (f16)(y[e] - (float)hh); }
;             *(f16x2*)(yh + (size_t)row * DM + c) = hi; if (WLO && write_lo) *(f16x2*)(yl + (size_t)row * DM + c) = lo; }
	v_div_scale_f32 v30, s[24:25], v2, v2, v17
	v_pk_fma_f32 v[28:29], v[28:29], v[28:29], v[32:33]
	v_rcp_f32_e32 v32, v30
	s_nop 0
	v_fma_f32 v33, -v30, v32, 1.0
	v_fmac_f32_e32 v32, v33, v32
	v_div_scale_f32 v33, vcc, v17, v2, v17
	v_mul_f32_e32 v34, v33, v32
	v_fma_f32 v35, -v30, v34, v33
	v_fmac_f32_e32 v34, v35, v32
	v_fma_f32 v30, -v30, v34, v33
	v_div_fmas_f32 v30, v30, v32, v34
	v_div_fixup_f32 v17, v30, v2, v17
	v_div_scale_f32 v30, s[24:25], v2, v2, v16
	v_rcp_f32_e32 v32, v30
	s_nop 0
	v_fma_f32 v33, -v30, v32, 1.0
	v_fmac_f32_e32 v32, v33, v32
	v_div_scale_f32 v33, vcc, v16, v2, v16
	v_mul_f32_e32 v34, v33, v32
	v_fma_f32 v35, -v30, v34, v33
	v_fmac_f32_e32 v34, v35, v32
	v_fma_f32 v30, -v30, v34, v33
	v_div_fmas_f32 v30, v30, v32, v34
	v_div_fixup_f32 v16, v30, v2, v16
	v_add_f32_e32 v2, v84, v31
	v_div_scale_f32 v30, s[24:25], v2, v2, v19
	v_rcp_f32_e32 v31, v30
	s_nop 0
	v_fma_f32 v32, -v30, v31, 1.0
	v_fmac_f32_e32 v31, v32, v31
	v_div_scale_f32 v32, vcc, v19, v2, v19
	v_mul_f32_e32 v33, v32, v31
	v_fma_f32 v34, -v30, v33, v32
	v_fmac_f32_e32 v33, v34, v31
	v_fma_f32 v30, -v30, v33, v32
	v_div_fmas_f32 v30, v30, v31, v33
	v_div_fixup_f32 v19, v30, v2, v19
	v_div_scale_f32 v30, s[24:25], v2, v2, v18
	v_rcp_f32_e32 v31, v30
	s_nop 0
	v_fma_f32 v32, -v30, v31, 1.0
	v_fmac_f32_e32 v31, v32, v31
	v_div_scale_f32 v32, vcc, v18, v2, v18
	v_mul_f32_e32 v33, v32, v31
	v_fma_f32 v34, -v30, v33, v32
	v_fmac_f32_e32 v33, v34, v31
	v_fma_f32 v30, -v30, v33, v32
	v_div_fmas_f32 v30, v30, v31, v33
	v_div_fixup_f32 v18, v30, v2, v18
	v_mov_b32_e32 v32, v19
	v_mov_b32_e32 v33, v17
	v_mov_b32_e32 v30, v18
	v_mov_b32_e32 v31, v16
	v_pk_mul_f32 v[32:33], v[32:33], v[32:33]
	v_add_f32_e32 v2, v28, v29
	v_pk_fma_f32 v[30:31], v[30:31], v[30:31], v[32:33]
	s_nop 0
	v_add_f32_e32 v2, v31, v2
	v_add_f32_e32 v2, v30, v2
	s_nop 1
	v_add_f32_dpp v2, v2, v2 quad_perm:[1,0,3,2] row_mask:0xf bank_mask:0xf bound_ctrl:1
	s_nop 1
	v_add_f32_dpp v2, v2, v2 quad_perm:[2,3,0,1] row_mask:0xf bank_mask:0xf bound_ctrl:1
	s_nop 1
	v_add_f32_dpp v2, v2, v2 row_half_mirror row_mask:0xf bank_mask:0xf bound_ctrl:1
	s_nop 1
	v_add_f32_dpp v2, v2, v2 row_mirror row_mask:0xf bank_mask:0xf bound_ctrl:1
	s_nop 0
	v_readlane_b32 s2, v2, 16
	v_readlane_b32 s9, v2, 48
	v_readlane_b32 s24, v2, 0
	v_readlane_b32 s25, v2, 32
	v_mov_b32_e32 v28, s2
	v_mov_b32_e32 v29, s9
	v_pk_add_f32 v[28:29], s[24:25], v[28:29]
	s_nop 0
	v_add_f32_e32 v2, v28, v29
	v_fmamk_f32 v2, v2, 0x3b000000, v234
	v_cmp_gt_f32_e32 vcc, s83, v2
	v_mul_f32_e32 v28, 0x4f800000, v2
	s_nop 0
	v_cndmask_b32_e32 v2, v2, v28, vcc
	v_sqrt_f32_e32 v28, v2
	s_nop 0
	v_add_u32_e32 v29, -1, v28
	v_fma_f32 v30, -v29, v28, v2
	v_cmp_ge_f32_e64 s[42:43], 0, v30
	v_add_u32_e32 v30, 1, v28
	s_nop 0
	v_cndmask_b32_e64 v29, v28, v29, s[42:43]
	v_fma_f32 v28, -v30, v28, v2
	v_cmp_lt_f32_e64 s[42:43], 0, v28
	s_nop 1
	v_cndmask_b32_e64 v28, v29, v30, s[42:43]
	v_mul_f32_e32 v29, 0x37800000, v28
	v_cndmask_b32_e32 v28, v28, v29, vcc
	v_cmp_class_f32_e32 vcc, v2, v235
	s_nop 1
	v_cndmask_b32_e32 v2, v28, v2, vcc
	v_div_scale_f32 v28, s[24:25], v2, v2, 1.0
	v_rcp_f32_e32 v29, v28
	s_nop 0
	v_fma_f32 v30, -v28, v29, 1.0
	v_fmac_f32_e32 v29, v30, v29
	v_div_scale_f32 v30, vcc, 1.0, v2, 1.0
	v_mul_f32_e32 v31, v30, v29
	v_fma_f32 v32, -v28, v31, v30
	v_fmac_f32_e32 v31, v32, v29
	v_fma_f32 v28, -v28, v31, v30
	v_div_fmas_f32 v28, v28, v29, v31
	v_div_fixup_f32 v2, v28, v2, 1.0
	s_nop 0
	v_pk_mul_f32 v[12:13], v[12:13], v[2:3] op_sel_hi:[1,0]
	v_pk_mul_f32 v[14:15], v[14:15], v[2:3] op_sel_hi:[1,0]
	v_pk_mul_f32 v[16:17], v[16:17], v[2:3] op_sel_hi:[1,0]
	s_nop 0
	s_nop 0
	s_nop 0
	v_pk_mul_f32 v[12:13], v[108:109], v[12:13]
	s_nop 0
	v_pk_mul_f32 v[12:13], v[12:13], s[96:97] op_sel_hi:[1,0]
	s_nop 0
	v_cvt_pk_f16_f32 v28, v12, v13
	v_lshl_add_u64 v[12:13], s[26:27], 0, v[50:51]
	v_add_co_u32_e32 v12, vcc, s77, v12
	s_add_u32 s26, s26, s12
	s_nop 0
	v_addc_co_u32_e32 v13, vcc, 0, v13, vcc
	global_store_dword v[12:13], v28, off offset:2048
	s_nop 0
	s_addc_u32 s27, s27, s13
	s_nop 0
	v_pk_mul_f32 v[14:15], v[110:111], v[14:15]
	s_nop 0
	v_pk_mul_f32 v[14:15], v[14:15], s[96:97] op_sel_hi:[1,0]
	s_nop 0
	v_cvt_pk_f16_f32 v14, v14, v15
	global_store_dword v[12:13], v14, off offset:2304
	s_nop 0
	s_nop 0
	s_nop 0
	v_pk_mul_f32 v[14:15], v[112:113], v[16:17]
	s_nop 0
	v_pk_mul_f32 v[14:15], v[14:15], s[96:97] op_sel_hi:[1,0]
	v_pk_mul_f32 v[16:17], v[18:19], v[2:3] op_sel_hi:[1,0]
	v_cvt_pk_f16_f32 v14, v14, v15
	global_store_dword v[12:13], v14, off offset:2560
	s_nop 0
	s_nop 0
	v_pk_mul_f32 v[14:15], v[16:17], v[114:115]
	s_nop 0
	v_pk_mul_f32 v[14:15], v[14:15], s[96:97] op_sel_hi:[1,0]
	s_nop 0
	v_cvt_pk_f16_f32 v2, v14, v15
	global_store_dword v[12:13], v2, off offset:2816
	s_nop 0
	s_nop 0
	s_nop 0
	s_nop 0
	s_waitcnt vmcnt(5)
	v_mov_b64_e32 v[70:71], v[56:57]
	v_mov_b64_e32 v[68:69], v[58:59]
	v_mov_b64_e32 v[66:67], v[60:61]
	v_mov_b64_e32 v[64:65], v[62:63]
	v_mov_b32_e32 v87, v80
	v_mov_b32_e32 v86, v81
	v_mov_b32_e32 v85, v82
	v_mov_b32_e32 v84, v83
	v_mov_b64_e32 v[34:35], v[22:23]
	v_mov_b64_e32 v[32:33], v[20:21]
	v_mov_b64_e32 v[30:31], v[26:27]
	v_mov_b64_e32 v[28:29], v[24:25]
	v_mov_b64_e32 v[18:19], v[10:11]
	v_mov_b64_e32 v[16:17], v[8:9]
	v_mov_b64_e32 v[14:15], v[6:7]
	v_mov_b64_e32 v[12:13], v[4:5]
	s_andn2_b64 exec, exec, s[20:21]
	s_cbranch_execz .LBB0_1058
